# attention units reordered so one XCC runs all 32 n-blocks of a (b,kh): K/V window rows and ctx rows reused in that XCC's L2
# baseline (speedup 1.0000x reference)
; #define LAS __attribute__((address_space(3)))
; #define AT_SYNC() do { asm volatile("s_waitcnt vmcnt(0) lgkmcnt(0)" ::: "memory"); __builtin_amdgcn_s_barrier(); asm volatile("" ::: "memory"); } while (0)
; __device__ __forceinline__ bool attn_unit(const Ptrs& P, LAS unsigned char* lds, int unit, int tid, int wave, int lane, bool pre, int nxt) {
;     const int n = unit & 31, kh = (unit >> 5) & 3, b = unit >> 7;
;     const int g = wave & 3, q0 = 64 * (wave >> 2), h = kh * 4 + g, r = lane & 31, hh = lane >> 5;
;     unsigned char* ws = P.ws;
;     bf16_t* Qb = (bf16_t*)(ws + WS_Q) + (size_t)(b * SEQ + n * 128 + q0) * DM + h * 64;
;     const bf16_t* Kg = (const bf16_t*)(ws + WS_K) + (size_t)b * SEQ * KVW + kh * 64; const bf16_t* Vg = (const bf16_t*)(ws + WS_VT) + (size_t)(b * 4 + kh) * 64 * SEQ;
;     const bf16_t* Kcg = (const bf16_t*)(ws + WS_KC) + (size_t)b * CTX * KVW + kh * 64; const bf16_t* Vcg = (const bf16_t*)(ws + WS_VCT) + (size_t)(b * 4 + kh) * 64 * CTX;
;     float mq = fabsf(P.qg[lane]), mk = fabsf(P.kg[lane]);
; #pragma unroll
;     for (int o = 1; o < 64; o <<= 1) { mq = fmaxf(mq, __shfl_xor(mq, o)); mk = fmaxf(mk, __shfl_xor(mk, o)); }
;     const float sink2 = P.sink[h] * LOG2E; const float mshift = fmaxf(64.0f * QSCALE * mq * mk, sink2);
;     bf16x8_t qf[2][4];
; #pragma unroll
;     for (int cb = 0; cb < 2; ++cb)
; #pragma unroll
;         for (int ds = 0; ds < 4; ++ds) qf[cb][ds] = __builtin_nontemporal_load((const bf16x8_t*)(Qb + (size_t)(32 * cb + r) * DM + 16 * ds + 8 * hh));
;     f32x16 o[2][2];
; #pragma unroll
;     for (int db = 0; db < 2; ++db)
; #pragma unroll
;         for (int cb = 0; cb < 2; ++cb)
; #pragma unroll
;             for (int i = 0; i < 16; ++i) o[db][cb][i] = 0.f;
;     float rs[2] = {0.f, 0.f};
;     f32x16 negm;
; #pragma unroll
;     for (int i = 0; i < 16; ++i) negm[i] = -mshift;
;     ...
;     if (!pre) { if (n == 0) AT_DMA(1); else AT_DMA(0); }
;     AT_SYNC();
;     const int n2 = nxt & 31; const bool pf = nxt >= 0 && n2 != 0;
.LBB9_305:
	s_cmp_lt_i32 s92, 4
	s_cselect_b64 s[2:3], -1, 0
	s_and_b64 s[22:23], s[2:3], s[0:1]
	s_andn2_b64 vcc, exec, s[22:23]
	s_cbranch_vccnz .LBB9_444
	v_writelane_b32 v251, s22, 33
	s_cmpk_gt_i32 s97, 0x1ff
	v_and_b32_e32 v171, 31, v208
	v_writelane_b32 v251, s23, 34
	v_writelane_b32 v251, s80, 35
	v_lshrrev_b32_e32 v184, 5, v170
	s_nop 0
	v_writelane_b32 v251, s81, 36
	v_writelane_b32 v251, s96, 37
	v_writelane_b32 v251, s83, 38
	v_writelane_b32 v251, s97, 39
	s_cbranch_scc1 .LBB9_413
	v_mbcnt_lo_u32_b32 v0, -1, 0
	v_mbcnt_hi_u32_b32 v0, -1, v0
	v_and_b32_e32 v1, 64, v0
	v_add_u32_e32 v1, 64, v1
	v_xor_b32_e32 v2, 1, v0
	v_cmp_lt_i32_e32 vcc, v2, v1
	s_bfe_u32 s0, s40, 0x20006
	v_writelane_b32 v251, s0, 40
	v_cndmask_b32_e32 v2, v0, v2, vcc
	v_lshlrev_b32_e32 v185, 2, v2
	v_xor_b32_e32 v2, 2, v0
	v_cmp_lt_i32_e32 vcc, v2, v1
	s_lshl_b32 s0, s50, 4
	s_and_b32 s33, s0, 0x3fffffc0
	v_cndmask_b32_e32 v2, v0, v2, vcc
	v_lshlrev_b32_e32 v186, 2, v2
	v_xor_b32_e32 v2, 4, v0
	v_cmp_lt_i32_e32 vcc, v2, v1
	s_cmpk_lt_u32 s40, 0x8c0
	s_cselect_b64 s[54:55], -1, 0
	v_cndmask_b32_e32 v2, v0, v2, vcc
	v_lshlrev_b32_e32 v187, 2, v2
	v_xor_b32_e32 v2, 8, v0
	v_cmp_lt_i32_e32 vcc, v2, v1
	s_or_b32 s2, s0, 63
	s_or_b32 s3, s33, 32
	v_cndmask_b32_e32 v2, v0, v2, vcc
	v_lshlrev_b32_e32 v188, 2, v2
	v_xor_b32_e32 v2, 16, v0
	v_cmp_lt_i32_e32 vcc, v2, v1
	v_or_b32_e32 v5, 32, v170
	v_lshlrev_b32_e32 v191, 4, v184
	v_cndmask_b32_e32 v2, v0, v2, vcc
	v_lshlrev_b32_e32 v189, 2, v2
	v_xor_b32_e32 v2, 32, v0
	v_cmp_lt_i32_e32 vcc, v2, v1
	v_mov_b32_e32 v1, 0
	v_mul_u32_u24_e32 v6, 0x110, v5
	v_cndmask_b32_e32 v0, v0, v2, vcc
	v_lshlrev_b32_e32 v190, 2, v0
	v_lshlrev_b32_e32 v0, 2, v184
	v_sub_u32_e32 v0, v171, v0
	v_cmp_lt_i32_e64 s[36:37], 10, v0
	v_cmp_gt_i32_e64 s[0:1], 1, v0
	v_cmp_gt_i32_e64 s[4:5], 2, v0
	v_writelane_b32 v251, s36, 41
	v_cmp_gt_i32_e64 s[6:7], 3, v0
	v_cmp_gt_i32_e64 s[8:9], 4, v0
	v_writelane_b32 v251, s37, 42
	v_cmp_lt_i32_e64 s[36:37], 15, v0
	v_cmp_gt_i32_e64 s[10:11], 9, v0
	v_cmp_gt_i32_e64 s[12:13], 10, v0
	v_writelane_b32 v251, s36, 43
	v_cmp_gt_i32_e64 s[14:15], 11, v0
	v_cmp_gt_i32_e64 s[16:17], 12, v0
	v_writelane_b32 v251, s37, 44
	v_cmp_lt_i32_e64 s[36:37], 16, v0
	v_cmp_gt_i32_e64 s[18:19], 17, v0
	v_cmp_gt_i32_e64 s[20:21], 18, v0
	v_writelane_b32 v251, s36, 45
	v_cmp_gt_i32_e64 s[22:23], 19, v0
	v_cmp_gt_i32_e64 s[24:25], 20, v0
	v_writelane_b32 v251, s37, 46
	v_cmp_lt_i32_e64 s[36:37], 17, v0
	v_cmp_gt_i32_e64 s[26:27], 25, v0
	v_cmp_gt_i32_e64 s[28:29], 26, v0
	v_writelane_b32 v251, s36, 47
	v_cmp_gt_i32_e64 s[30:31], 27, v0
	v_cmp_gt_i32_e64 s[34:35], 28, v0
	v_writelane_b32 v251, s37, 48
	v_cmp_lt_i32_e64 s[36:37], 18, v0
	v_cmp_lt_i32_e64 s[56:57], -1, v0
	v_cmp_lt_i32_e64 s[86:87], 0, v0
	v_writelane_b32 v251, s36, 49
	v_cmp_lt_i32_e64 s[60:61], 1, v0
	v_cmp_lt_i32_e64 s[62:63], 2, v0
	v_writelane_b32 v251, s37, 50
	v_cmp_lt_i32_e64 s[36:37], 23, v0
	v_cmp_lt_i32_e64 s[64:65], 7, v0
	v_cmp_lt_i32_e64 s[66:67], 8, v0
	v_writelane_b32 v251, s36, 51
	v_cmp_lt_i32_e64 s[72:73], 9, v0
	v_lshlrev_b32_e32 v4, 3, v184
	v_writelane_b32 v251, s37, 52
	v_cmp_lt_i32_e64 s[36:37], 24, v0
	v_mul_u32_u24_e32 v3, 0x110, v171
	v_lshlrev_b32_e32 v2, 10, v171
	v_writelane_b32 v251, s36, 53
	s_movk_i32 s52, 0x110
	v_add3_u32 v3, v3, v191, 0
	v_writelane_b32 v251, s37, 54
	v_cmp_lt_i32_e64 s[36:37], 25, v0
	v_lshlrev_b32_e32 v176, 1, v4
	s_mov_b32 s77, 0
	v_writelane_b32 v251, s36, 55
	v_add_u32_e32 v195, 0x4800, v3
	v_add_u32_e32 v198, 0xd400, v3
	v_writelane_b32 v251, s37, 56
	v_cmp_lt_i32_e64 s[36:37], 26, v0
	v_lshlrev_b32_e32 v0, 2, v170
	v_mad_u32_u24 v200, v5, s52, 0
	v_writelane_b32 v251, s36, 57
	v_mad_u32_u24 v201, v171, s52, 0
	s_mov_b64 s[68:69], 0
	v_writelane_b32 v251, s37, 58
	s_add_u32 s36, s90, 0x6200000
	v_writelane_b32 v251, s36, 59
	s_addc_u32 s36, s91, 0
	v_writelane_b32 v251, s36, 60
	s_add_u32 s36, s90, 0x7200000
	v_writelane_b32 v251, s36, 61
	s_addc_u32 s36, s91, 0
	v_writelane_b32 v251, s36, 62
	v_mov_b32_e32 v178, v176
	v_readlane_b32 s36, v251, 16
	s_add_u32 s36, s90, 0x4200000
	v_readlane_b32 s37, v251, 17
	v_readlane_b32 s38, v251, 18
	v_readlane_b32 s39, v251, 19
	v_readlane_b32 s40, v251, 20
	v_readlane_b32 s41, v251, 21
	v_readlane_b32 s42, v251, 22
	v_readlane_b32 s43, v251, 23
	v_readlane_b32 s44, v251, 24
	v_readlane_b32 s45, v251, 25
	v_readlane_b32 s46, v251, 26
	v_readlane_b32 s47, v251, 27
	v_readlane_b32 s48, v251, 28
	v_readlane_b32 s49, v251, 29
	v_readlane_b32 s50, v251, 30
	v_readlane_b32 s51, v251, 31
	v_writelane_b32 v251, s36, 63
	s_addc_u32 s36, s91, 0
	v_writelane_b32 v250, s36, 0
	s_add_u32 s36, s90, 0x6a00000
	v_writelane_b32 v250, s36, 1
	s_addc_u32 s36, s91, 0
	v_writelane_b32 v250, s36, 2
	s_add_u32 s36, s90, 0x7280000
	v_writelane_b32 v250, s36, 3
	s_addc_u32 s36, s91, 0
	v_writelane_b32 v250, s36, 4
	s_add_u32 s36, s90, 0x2000000
	v_writelane_b32 v250, s36, 5
	s_addc_u32 s36, s91, 0
	v_lshl_add_u64 v[172:173], s[40:41], 0, v[0:1]
	v_writelane_b32 v250, s36, 6
	s_add_i32 s40, 0, 0x11800
	s_add_i32 s76, 0, 0x16000
	v_writelane_b32 v250, s40, 7
	v_writelane_b32 v250, s76, 8
	v_writelane_b32 v250, s88, 9
	v_lshl_add_u64 v[174:175], s[42:43], 0, v[0:1]
	v_readlane_b32 s36, v251, 32
	v_writelane_b32 v250, s89, 10
	v_writelane_b32 v250, s90, 11
	v_writelane_b32 v250, s91, 12
	v_add3_u32 v0, v6, v191, 0
	v_mul_u32_u24_e32 v6, 0x90, v171
	v_writelane_b32 v250, s92, 13
	v_lshl_or_b32 v192, s36, 6, v170
	s_movk_i32 s37, 0x90
	v_add3_u32 v196, v6, v191, 0
	v_writelane_b32 v250, s93, 14
	v_add_u32_e32 v193, 0xfffffb80, v192
	v_add_u32_e32 v194, 0x4800, v0
	v_add_u32_e32 v197, 0xd400, v0
	v_add_u32_e32 v199, 0x8c00, v196
	v_mad_u32_u24 v202, v171, s37, 0
	v_mov_b32_e32 v179, v1
	v_lshlrev_b32_e32 v180, 1, v2
	v_mov_b32_e32 v181, v1
	s_mov_b32 s36, 0xf0f0f0f1
	s_movk_i32 s37, 0xffef
	s_movk_i32 s38, 0x490
	s_mov_b32 s39, 0x38e38e39
	v_readlane_b32 s42, v251, 39
	s_cmpk_lg_i32 s94, 0x100
	s_cbranch_scc1 .Lremap_skip
	s_and_b32 s43, s42, 7
	s_lshl_b32 s43, s43, 5
	s_lshr_b32 s42, s42, 3
	s_or_b32 s42, s42, s43
.Lremap_skip:
	v_writelane_b32 v250, s94, 15
	v_writelane_b32 v250, s95, 16
